# gate/up epilogue stores nt (shorter store acknowledge in front of the next unit's counted waits)
# baseline (speedup 1.0000x reference)
.LBB0_380:
	v_mad_u64_u32 v[144:145], s[48:49], s82, v140, 0
	v_readlane_b32 s48, v232, 2
	s_waitcnt lgkmcnt(0)
	v_lshl_or_b32 v142, s69, 7, v148
	v_add3_u32 v145, v145, v150, v151
	v_readlane_b32 s49, v232, 3
	v_ashrrev_i32_e32 v143, 31, v142
	v_pk_mul_f32 v[120:121], v[120:121], v[128:129]
	v_lshl_add_u64 v[144:145], v[144:145], 1, s[48:49]
	v_pk_mul_f32 v[118:119], v[118:119], v[126:127]
	v_pk_mul_f32 v[124:125], v[116:117], v[124:125]
	v_pk_mul_f32 v[116:117], v[114:115], v[122:123]
	v_lshl_add_u64 v[144:145], v[142:143], 1, v[144:145]
	v_cvt_pk_bf16_f32 v114, v118, v119
	v_cvt_pk_bf16_f32 v115, v120, v121
	v_cvt_pk_bf16_f32 v116, v116, v117
	v_cvt_pk_bf16_f32 v117, v124, v125
	s_and_b64 vcc, exec, s[42:43]
	global_store_dwordx4 v[144:145], v[114:117], off nt
	s_cbranch_vccnz .LBB0_382
	s_nop 0
	v_mul_f32_e32 v115, 0xbfb8aa3b, v106
	v_exp_f32_e32 v115, v115
	v_mul_f32_e32 v114, 0xbfb8aa3b, v110
	v_exp_f32_e32 v114, v114
	v_mul_f32_e32 v119, 0xbfb8aa3b, v108
	v_add_f32_e32 v115, 1.0, v115
	v_rcp_f32_e32 v116, v115
	v_mul_f32_e32 v115, 0xbfb8aa3b, v111
	v_exp_f32_e32 v115, v115
	v_add_f32_e32 v114, 1.0, v114
	v_exp_f32_e32 v119, v119
	v_rcp_f32_e32 v114, v114
	v_add_f32_e32 v115, 1.0, v115
	v_rcp_f32_e32 v115, v115
	v_add_f32_e32 v119, 1.0, v119
	v_mul_f32_e32 v117, 0xbfb8aa3b, v107
	v_mul_f32_e32 v118, 0xbfb8aa3b, v112
	v_rcp_f32_e32 v120, v119
	v_mul_f32_e32 v119, 0xbfb8aa3b, v113
	v_pk_mul_f32 v[110:111], v[110:111], v[114:115]
	v_mul_f32_e32 v114, 0xbfb8aa3b, v109
	v_exp_f32_e32 v117, v117
	v_exp_f32_e32 v118, v118
	v_exp_f32_e32 v119, v119
	v_exp_f32_e32 v114, v114
	v_add_f32_e32 v117, 1.0, v117
	v_add_f32_e32 v118, 1.0, v118
	v_add_f32_e32 v119, 1.0, v119
	v_add_f32_e32 v114, 1.0, v114
	v_rcp_f32_e32 v117, v117
	v_rcp_f32_e32 v118, v118
	v_rcp_f32_e32 v119, v119
	v_rcp_f32_e32 v121, v114
	v_pk_mul_f32 v[106:107], v[106:107], v[116:117]
	v_pk_mul_f32 v[112:113], v[112:113], v[118:119]
	v_pk_mul_f32 v[108:109], v[108:109], v[120:121]
.LBB0_382:
	s_nop 0
	v_or_b32_e32 v114, 16, v140
	v_mul_lo_u32 v116, s83, v114
	v_mad_u64_u32 v[114:115], s[48:49], s82, v114, 0
	v_readlane_b32 s48, v232, 2
	v_add3_u32 v115, v115, v150, v116
	v_readlane_b32 s49, v232, 3
	v_pk_mul_f32 v[104:105], v[104:105], v[112:113]
	v_pk_mul_f32 v[102:103], v[102:103], v[110:111]
	v_lshl_add_u64 v[114:115], v[114:115], 1, s[48:49]
	v_pk_mul_f32 v[108:109], v[100:101], v[108:109]
	v_pk_mul_f32 v[100:101], v[98:99], v[106:107]
	v_lshl_add_u64 v[114:115], v[142:143], 1, v[114:115]
	v_cvt_pk_bf16_f32 v98, v102, v103
	v_cvt_pk_bf16_f32 v99, v104, v105
	v_cvt_pk_bf16_f32 v100, v100, v101
	v_cvt_pk_bf16_f32 v101, v108, v109
	s_and_b64 vcc, exec, s[42:43]
	global_store_dwordx4 v[114:115], v[98:101], off nt
	s_cbranch_vccnz .LBB0_384
	s_nop 0
	v_mul_f32_e32 v99, 0xbfb8aa3b, v88
	v_exp_f32_e32 v99, v99
	v_mul_f32_e32 v98, 0xbfb8aa3b, v92
	v_exp_f32_e32 v98, v98
	v_mul_f32_e32 v103, 0xbfb8aa3b, v90
	v_add_f32_e32 v99, 1.0, v99
	v_rcp_f32_e32 v100, v99
	v_mul_f32_e32 v99, 0xbfb8aa3b, v93
	v_exp_f32_e32 v99, v99
	v_add_f32_e32 v98, 1.0, v98
	v_exp_f32_e32 v103, v103
	v_rcp_f32_e32 v98, v98
	v_add_f32_e32 v99, 1.0, v99
	v_rcp_f32_e32 v99, v99
	v_add_f32_e32 v103, 1.0, v103
	v_mul_f32_e32 v101, 0xbfb8aa3b, v89
	v_mul_f32_e32 v102, 0xbfb8aa3b, v94
	v_rcp_f32_e32 v104, v103
	v_mul_f32_e32 v103, 0xbfb8aa3b, v95
	v_pk_mul_f32 v[92:93], v[92:93], v[98:99]
	v_mul_f32_e32 v98, 0xbfb8aa3b, v91
	v_exp_f32_e32 v101, v101
	v_exp_f32_e32 v102, v102
	v_exp_f32_e32 v103, v103
	v_exp_f32_e32 v98, v98
	v_add_f32_e32 v101, 1.0, v101
	v_add_f32_e32 v102, 1.0, v102
	v_add_f32_e32 v103, 1.0, v103
	v_add_f32_e32 v98, 1.0, v98
	v_rcp_f32_e32 v101, v101
	v_rcp_f32_e32 v102, v102
	v_rcp_f32_e32 v103, v103
	v_rcp_f32_e32 v105, v98
	v_pk_mul_f32 v[88:89], v[88:89], v[100:101]
	v_pk_mul_f32 v[94:95], v[94:95], v[102:103]
	v_pk_mul_f32 v[90:91], v[90:91], v[104:105]
.LBB0_384:
	s_nop 0
	v_or_b32_e32 v98, 32, v140
	v_mul_lo_u32 v100, s83, v98
	v_mad_u64_u32 v[98:99], s[48:49], s82, v98, 0
	v_readlane_b32 s48, v232, 2
	v_add3_u32 v99, v99, v150, v100
	v_readlane_b32 s49, v232, 3
	v_pk_mul_f32 v[86:87], v[86:87], v[94:95]
	v_pk_mul_f32 v[84:85], v[84:85], v[92:93]
	v_lshl_add_u64 v[98:99], v[98:99], 1, s[48:49]
	v_pk_mul_f32 v[90:91], v[82:83], v[90:91]
	v_pk_mul_f32 v[82:83], v[80:81], v[88:89]
	v_lshl_add_u64 v[98:99], v[142:143], 1, v[98:99]
	v_cvt_pk_bf16_f32 v80, v84, v85
	v_cvt_pk_bf16_f32 v81, v86, v87
	v_cvt_pk_bf16_f32 v82, v82, v83
	v_cvt_pk_bf16_f32 v83, v90, v91
	s_and_b64 vcc, exec, s[42:43]
	global_store_dwordx4 v[98:99], v[80:83], off nt
	s_cbranch_vccnz .LBB0_386
	s_nop 0
	v_mul_f32_e32 v81, 0xbfb8aa3b, v72
	v_exp_f32_e32 v81, v81
	v_mul_f32_e32 v80, 0xbfb8aa3b, v76
	v_exp_f32_e32 v80, v80
	v_mul_f32_e32 v85, 0xbfb8aa3b, v74
	v_add_f32_e32 v81, 1.0, v81
	v_rcp_f32_e32 v82, v81
	v_mul_f32_e32 v81, 0xbfb8aa3b, v77
	v_exp_f32_e32 v81, v81
	v_add_f32_e32 v80, 1.0, v80
	v_exp_f32_e32 v85, v85
	v_rcp_f32_e32 v80, v80
	v_add_f32_e32 v81, 1.0, v81
	v_rcp_f32_e32 v81, v81
	v_add_f32_e32 v85, 1.0, v85
	v_mul_f32_e32 v83, 0xbfb8aa3b, v73
	v_mul_f32_e32 v84, 0xbfb8aa3b, v78
	v_rcp_f32_e32 v86, v85
	v_mul_f32_e32 v85, 0xbfb8aa3b, v79
	v_pk_mul_f32 v[76:77], v[76:77], v[80:81]
	v_mul_f32_e32 v80, 0xbfb8aa3b, v75
	v_exp_f32_e32 v83, v83
	v_exp_f32_e32 v84, v84
	v_exp_f32_e32 v85, v85
	v_exp_f32_e32 v80, v80
	v_add_f32_e32 v83, 1.0, v83
	v_add_f32_e32 v84, 1.0, v84
	v_add_f32_e32 v85, 1.0, v85
	v_add_f32_e32 v80, 1.0, v80
	v_rcp_f32_e32 v83, v83
	v_rcp_f32_e32 v84, v84
	v_rcp_f32_e32 v85, v85
	v_rcp_f32_e32 v87, v80
	v_pk_mul_f32 v[72:73], v[72:73], v[82:83]
	v_pk_mul_f32 v[78:79], v[78:79], v[84:85]
	v_pk_mul_f32 v[74:75], v[74:75], v[86:87]
.LBB0_386:
	s_nop 0
	v_or_b32_e32 v80, 48, v140
	v_mul_lo_u32 v82, s83, v80
	v_mad_u64_u32 v[80:81], s[48:49], s82, v80, 0
	v_readlane_b32 s48, v232, 2
	v_add3_u32 v81, v81, v150, v82
	v_readlane_b32 s49, v232, 3
	v_pk_mul_f32 v[70:71], v[70:71], v[78:79]
	v_pk_mul_f32 v[68:69], v[68:69], v[76:77]
	v_lshl_add_u64 v[80:81], v[80:81], 1, s[48:49]
	v_pk_mul_f32 v[74:75], v[66:67], v[74:75]
	v_pk_mul_f32 v[66:67], v[64:65], v[72:73]
	v_lshl_add_u64 v[80:81], v[142:143], 1, v[80:81]
	v_cvt_pk_bf16_f32 v64, v68, v69
	v_cvt_pk_bf16_f32 v65, v70, v71
	v_cvt_pk_bf16_f32 v66, v66, v67
	v_cvt_pk_bf16_f32 v67, v74, v75
	s_and_b64 vcc, exec, s[42:43]
	global_store_dwordx4 v[80:81], v[64:67], off nt
	s_cbranch_vccnz .LBB0_388
	s_nop 0
	v_mul_f32_e32 v65, 0xbfb8aa3b, v56
	v_exp_f32_e32 v65, v65
	v_mul_f32_e32 v64, 0xbfb8aa3b, v60
	v_exp_f32_e32 v64, v64
	v_mul_f32_e32 v69, 0xbfb8aa3b, v58
	v_add_f32_e32 v65, 1.0, v65
	v_rcp_f32_e32 v66, v65
	v_mul_f32_e32 v65, 0xbfb8aa3b, v61
	v_exp_f32_e32 v65, v65
	v_add_f32_e32 v64, 1.0, v64
	v_exp_f32_e32 v69, v69
	v_rcp_f32_e32 v64, v64
	v_add_f32_e32 v65, 1.0, v65
	v_rcp_f32_e32 v65, v65
	v_add_f32_e32 v69, 1.0, v69
	v_mul_f32_e32 v67, 0xbfb8aa3b, v57
	v_mul_f32_e32 v68, 0xbfb8aa3b, v62
	v_rcp_f32_e32 v70, v69
	v_mul_f32_e32 v69, 0xbfb8aa3b, v63
	v_pk_mul_f32 v[60:61], v[60:61], v[64:65]
	v_mul_f32_e32 v64, 0xbfb8aa3b, v59
	v_exp_f32_e32 v67, v67
	v_exp_f32_e32 v68, v68
	v_exp_f32_e32 v69, v69
	v_exp_f32_e32 v64, v64
	v_add_f32_e32 v67, 1.0, v67
	v_add_f32_e32 v68, 1.0, v68
	v_add_f32_e32 v69, 1.0, v69
	v_add_f32_e32 v64, 1.0, v64
	v_rcp_f32_e32 v67, v67
	v_rcp_f32_e32 v68, v68
	v_rcp_f32_e32 v69, v69
	v_rcp_f32_e32 v71, v64
	v_pk_mul_f32 v[56:57], v[56:57], v[66:67]
	v_pk_mul_f32 v[62:63], v[62:63], v[68:69]
	v_pk_mul_f32 v[58:59], v[58:59], v[70:71]
.LBB0_388:
	s_nop 0
	v_add_u32_e32 v64, 0x80, v140
	v_ashrrev_i32_e32 v65, 31, v64
	v_mul_lo_u32 v66, s82, v65
	v_mul_lo_u32 v67, s83, v64
	v_mad_u64_u32 v[64:65], s[48:49], s82, v64, 0
	v_readlane_b32 s48, v232, 2
	v_add3_u32 v65, v65, v66, v67
	v_readlane_b32 s49, v232, 3
	v_pk_mul_f32 v[54:55], v[54:55], v[62:63]
	v_pk_mul_f32 v[52:53], v[52:53], v[60:61]
	v_lshl_add_u64 v[64:65], v[64:65], 1, s[48:49]
	v_pk_mul_f32 v[58:59], v[50:51], v[58:59]
	v_pk_mul_f32 v[50:51], v[48:49], v[56:57]
	v_lshl_add_u64 v[64:65], v[142:143], 1, v[64:65]
	v_cvt_pk_bf16_f32 v48, v52, v53
	v_cvt_pk_bf16_f32 v49, v54, v55
	v_cvt_pk_bf16_f32 v50, v50, v51
	v_cvt_pk_bf16_f32 v51, v58, v59
	s_and_b64 vcc, exec, s[42:43]
	global_store_dwordx4 v[64:65], v[48:51], off nt
	s_cbranch_vccnz .LBB0_390
	s_nop 0
	v_mul_f32_e32 v49, 0xbfb8aa3b, v40
	v_exp_f32_e32 v49, v49
	v_mul_f32_e32 v48, 0xbfb8aa3b, v44
	v_exp_f32_e32 v48, v48
	v_mul_f32_e32 v53, 0xbfb8aa3b, v42
	v_add_f32_e32 v49, 1.0, v49
	v_rcp_f32_e32 v50, v49
	v_mul_f32_e32 v49, 0xbfb8aa3b, v45
	v_exp_f32_e32 v49, v49
	v_add_f32_e32 v48, 1.0, v48
	v_exp_f32_e32 v53, v53
	v_rcp_f32_e32 v48, v48
	v_add_f32_e32 v49, 1.0, v49
	v_rcp_f32_e32 v49, v49
	v_add_f32_e32 v53, 1.0, v53
	v_mul_f32_e32 v51, 0xbfb8aa3b, v41
	v_mul_f32_e32 v52, 0xbfb8aa3b, v46
	v_rcp_f32_e32 v54, v53
	v_mul_f32_e32 v53, 0xbfb8aa3b, v47
	v_pk_mul_f32 v[44:45], v[44:45], v[48:49]
	v_mul_f32_e32 v48, 0xbfb8aa3b, v43
	v_exp_f32_e32 v51, v51
	v_exp_f32_e32 v52, v52
	v_exp_f32_e32 v53, v53
	v_exp_f32_e32 v48, v48
	v_add_f32_e32 v51, 1.0, v51
	v_add_f32_e32 v52, 1.0, v52
	v_add_f32_e32 v53, 1.0, v53
	v_add_f32_e32 v48, 1.0, v48
	v_rcp_f32_e32 v51, v51
	v_rcp_f32_e32 v52, v52
	v_rcp_f32_e32 v53, v53
	v_rcp_f32_e32 v55, v48
	v_pk_mul_f32 v[40:41], v[40:41], v[50:51]
	v_pk_mul_f32 v[46:47], v[46:47], v[52:53]
	v_pk_mul_f32 v[42:43], v[42:43], v[54:55]
.LBB0_390:
	s_nop 0
	v_add_u32_e32 v48, 0x90, v140
	v_ashrrev_i32_e32 v49, 31, v48
	v_mul_lo_u32 v50, s82, v49
	v_mul_lo_u32 v51, s83, v48
	v_mad_u64_u32 v[48:49], s[48:49], s82, v48, 0
	v_readlane_b32 s48, v232, 2
	v_add3_u32 v49, v49, v50, v51
	v_readlane_b32 s49, v232, 3
	v_pk_mul_f32 v[38:39], v[38:39], v[46:47]
	v_pk_mul_f32 v[36:37], v[36:37], v[44:45]
	v_lshl_add_u64 v[48:49], v[48:49], 1, s[48:49]
	v_pk_mul_f32 v[42:43], v[34:35], v[42:43]
	v_pk_mul_f32 v[34:35], v[32:33], v[40:41]
	v_lshl_add_u64 v[48:49], v[142:143], 1, v[48:49]
	v_cvt_pk_bf16_f32 v32, v36, v37
	v_cvt_pk_bf16_f32 v33, v38, v39
	v_cvt_pk_bf16_f32 v34, v34, v35
	v_cvt_pk_bf16_f32 v35, v42, v43
	s_and_b64 vcc, exec, s[42:43]
	global_store_dwordx4 v[48:49], v[32:35], off nt
	s_cbranch_vccnz .LBB0_392
	s_nop 0
	v_mul_f32_e32 v33, 0xbfb8aa3b, v24
	v_exp_f32_e32 v33, v33
	v_mul_f32_e32 v32, 0xbfb8aa3b, v28
	v_exp_f32_e32 v32, v32
	v_mul_f32_e32 v37, 0xbfb8aa3b, v26
	v_add_f32_e32 v33, 1.0, v33
	v_rcp_f32_e32 v34, v33
	v_mul_f32_e32 v33, 0xbfb8aa3b, v29
	v_exp_f32_e32 v33, v33
	v_add_f32_e32 v32, 1.0, v32
	v_exp_f32_e32 v37, v37
	v_rcp_f32_e32 v32, v32
	v_add_f32_e32 v33, 1.0, v33
	v_rcp_f32_e32 v33, v33
	v_add_f32_e32 v37, 1.0, v37
	v_mul_f32_e32 v35, 0xbfb8aa3b, v25
	v_mul_f32_e32 v36, 0xbfb8aa3b, v30
	v_rcp_f32_e32 v38, v37
	v_mul_f32_e32 v37, 0xbfb8aa3b, v31
	v_pk_mul_f32 v[28:29], v[28:29], v[32:33]
	v_mul_f32_e32 v32, 0xbfb8aa3b, v27
	v_exp_f32_e32 v35, v35
	v_exp_f32_e32 v36, v36
	v_exp_f32_e32 v37, v37
	v_exp_f32_e32 v32, v32
	v_add_f32_e32 v35, 1.0, v35
	v_add_f32_e32 v36, 1.0, v36
	v_add_f32_e32 v37, 1.0, v37
	v_add_f32_e32 v32, 1.0, v32
	v_rcp_f32_e32 v35, v35
	v_rcp_f32_e32 v36, v36
	v_rcp_f32_e32 v37, v37
	v_rcp_f32_e32 v39, v32
	v_pk_mul_f32 v[24:25], v[24:25], v[34:35]
	v_pk_mul_f32 v[30:31], v[30:31], v[36:37]
	v_pk_mul_f32 v[26:27], v[26:27], v[38:39]
.LBB0_392:
	s_nop 0
	v_add_u32_e32 v32, 0xa0, v140
	v_ashrrev_i32_e32 v33, 31, v32
	v_mul_lo_u32 v34, s82, v33
	v_mul_lo_u32 v35, s83, v32
	v_mad_u64_u32 v[32:33], s[48:49], s82, v32, 0
	v_readlane_b32 s48, v232, 2
	v_add3_u32 v33, v33, v34, v35
	v_readlane_b32 s49, v232, 3
	v_pk_mul_f32 v[22:23], v[22:23], v[30:31]
	v_pk_mul_f32 v[20:21], v[20:21], v[28:29]
	v_lshl_add_u64 v[32:33], v[32:33], 1, s[48:49]
	v_pk_mul_f32 v[26:27], v[18:19], v[26:27]
	v_pk_mul_f32 v[18:19], v[16:17], v[24:25]
	v_lshl_add_u64 v[32:33], v[142:143], 1, v[32:33]
	v_cvt_pk_bf16_f32 v16, v20, v21
	v_cvt_pk_bf16_f32 v17, v22, v23
	v_cvt_pk_bf16_f32 v18, v18, v19
	v_cvt_pk_bf16_f32 v19, v26, v27
	s_and_b64 vcc, exec, s[42:43]
	global_store_dwordx4 v[32:33], v[16:19], off nt
	s_cbranch_vccnz .LBB0_394
	s_nop 0
	v_mul_f32_e32 v17, 0xbfb8aa3b, v8
	v_exp_f32_e32 v17, v17
	v_mul_f32_e32 v16, 0xbfb8aa3b, v12
	v_exp_f32_e32 v16, v16
	v_mul_f32_e32 v21, 0xbfb8aa3b, v10
	v_add_f32_e32 v17, 1.0, v17
	v_rcp_f32_e32 v18, v17
	v_mul_f32_e32 v17, 0xbfb8aa3b, v13
	v_exp_f32_e32 v17, v17
	v_add_f32_e32 v16, 1.0, v16
	v_exp_f32_e32 v21, v21
	v_rcp_f32_e32 v16, v16
	v_add_f32_e32 v17, 1.0, v17
	v_rcp_f32_e32 v17, v17
	v_add_f32_e32 v21, 1.0, v21
	v_mul_f32_e32 v19, 0xbfb8aa3b, v9
	v_mul_f32_e32 v20, 0xbfb8aa3b, v14
	v_rcp_f32_e32 v22, v21
	v_mul_f32_e32 v21, 0xbfb8aa3b, v15
	v_pk_mul_f32 v[12:13], v[12:13], v[16:17]
	v_mul_f32_e32 v16, 0xbfb8aa3b, v11
	v_exp_f32_e32 v19, v19
	v_exp_f32_e32 v20, v20
	v_exp_f32_e32 v21, v21
	v_exp_f32_e32 v16, v16
	v_add_f32_e32 v19, 1.0, v19
	v_add_f32_e32 v20, 1.0, v20
	v_add_f32_e32 v21, 1.0, v21
	v_add_f32_e32 v16, 1.0, v16
	v_rcp_f32_e32 v19, v19
	v_rcp_f32_e32 v20, v20
	v_rcp_f32_e32 v21, v21
	v_rcp_f32_e32 v23, v16
	v_pk_mul_f32 v[8:9], v[8:9], v[18:19]
	v_pk_mul_f32 v[14:15], v[14:15], v[20:21]
	v_pk_mul_f32 v[10:11], v[10:11], v[22:23]
.LBB0_394:
	s_nop 0
	v_add_u32_e32 v16, 0xb0, v140
	v_ashrrev_i32_e32 v17, 31, v16
	v_mul_lo_u32 v18, s82, v17
	v_mul_lo_u32 v19, s83, v16
	v_mad_u64_u32 v[16:17], s[42:43], s82, v16, 0
	v_readlane_b32 s42, v232, 2
	v_add3_u32 v17, v17, v18, v19
	v_readlane_b32 s43, v232, 3
	v_pk_mul_f32 v[6:7], v[6:7], v[14:15]
	v_pk_mul_f32 v[4:5], v[4:5], v[12:13]
	v_lshl_add_u64 v[16:17], v[16:17], 1, s[42:43]
	v_pk_mul_f32 v[10:11], v[2:3], v[10:11]
	v_pk_mul_f32 v[2:3], v[0:1], v[8:9]
	v_lshl_add_u64 v[16:17], v[142:143], 1, v[16:17]
	v_cvt_pk_bf16_f32 v0, v4, v5
	v_cvt_pk_bf16_f32 v1, v6, v7
	v_cvt_pk_bf16_f32 v2, v2, v3
	v_cvt_pk_bf16_f32 v3, v10, v11
	global_store_dwordx4 v[16:17], v[0:3], off nt
	s_and_b64 vcc, exec, s[40:41]
	s_mov_b64 s[40:41], -1
	s_cbranch_vccnz .LBB0_325
